# hgB loop re-scheduled so the wait for a prefetched group counts the four ST stores issued after it (vmcnt 12), and hgA's steady-state top-of-chunk waits count the 32 UT stores (vmcnt 35/33/32, first i
# speedup vs baseline: 1.0026x; 1.0026x over previous
; DI void hg_phase_a(const P& p, const bf16_t* PROJ, float* UT, float* DEC, LAS unsigned char* L) {
;     ...
;     for (int ch = blockIdx.x; ch < 2048; ch += gridDim.x) {
;         const int bh = ch >> 6, hh = bh & 7;
;         __syncthreads();
;         hg_raw_store(rawf, tid, rf); hg_raw_store(rawv, tid, rv);
.LBB0_285:
	s_add_i32 s34, s18, s86
	s_cmpk_gt_i32 s34, 0x7ff
	s_cselect_b64 s[16:17], -1, 0
	s_and_b64 vcc, exec, s[16:17]
	s_waitcnt lgkmcnt(0)
	s_barrier
	s_waitcnt vmcnt(35)
	ds_write_b128 v57, v[32:35] offset:40960
	s_waitcnt vmcnt(33)
	ds_write_b128 v57, v[40:43] offset:49664
	ds_write_b128 v57, v[36:39] offset:58368
	s_waitcnt vmcnt(32)
	ds_write_b128 v58, v[44:47] offset:8704
	s_branch .Lhga_join

; DI void hg_phase_a(const P& p, const bf16_t* PROJ, float* UT, float* DEC, LAS unsigned char* L) {
;     ...
;         __syncthreads();
;         hg_raw_store(rawf, tid, rf); hg_raw_store(rawv, tid, rv);
;         if (ch + (int)gridDim.x < 2048) { hg_raw_load(PROJ, ch + gridDim.x, 4096, roff, rf); hg_raw_load(PROJ, ch + gridDim.x, 5120, roff, rv); }
.Lhga_join:
	s_and_b32 s19, s24, 0x380
	v_or_b32_e32 v92, s19, v56
	v_lshlrev_b32_e32 v92, 2, v92
	s_add_u32 s100, s14, 0x1000
	s_addc_u32 s101, s15, 0
	global_load_dword v90, v92, s[14:15]
	global_load_dword v91, v92, s[100:101]
	s_cbranch_vccnz .Lhga_nopf
	s_ashr_i32 s20, s34, 9
	s_ashr_i32 s21, s20, 31
	s_lshl_b64 s[20:21], s[20:21], 12
	s_and_b32 s19, s27, 0xfc0
	s_or_b32 s19, s20, s19
	s_mul_i32 s20, s21, 0x3800
	s_mul_hi_u32 s21, s19, 0x3800
	s_add_i32 s21, s21, s20
	s_mulk_i32 s19, 0x3800
	s_add_u32 s19, s22, s19
	s_addc_u32 s21, s23, s21
	s_add_i32 s20, s26, s24
	s_and_b32 s20, s20, 0x380
	s_lshl_b32 s20, s20, 1
	s_add_u32 s20, s19, s20
	s_addc_u32 s21, s21, 0
	v_lshl_add_u64 v[0:1], v[50:51], 1, s[20:21]
	v_add_co_u32_e32 v2, vcc, 0x2000, v0
	s_nop 1
	v_addc_co_u32_e32 v3, vcc, 0, v1, vcc
	v_add_co_u32_e32 v0, vcc, 0x72000, v0
	s_nop 1
	v_addc_co_u32_e32 v1, vcc, 0, v1, vcc
	global_load_dwordx4 v[32:35], v[2:3], off
	global_load_dwordx4 v[36:39], v[2:3], off offset:2048
	global_load_dwordx4 v[40:43], v[0:1], off
	global_load_dwordx4 v[44:47], v[0:1], off offset:2048
	s_branch .LBB0_287

; __device__ __forceinline__ int opaque_tid() { int t = threadIdx.x; asm volatile("" : "+v"(t)); return t; }
; DI unsigned pk2(float lo, float hi) { return pg8::cvt_pk_bf16(lo, hi); }
; DI void hg_phase_b(const float* UT, const float* DEC, bf16_t* ST) {
;     for (int idx = blockIdx.x * 512 + opaque_tid(); idx < 32 * 4096; idx += gridDim.x * 512) {
;         const int bh = idx >> 12, rem = idx & 4095, dv = rem >> 5, dk4 = (rem & 31) * 4;
;         f32x4 st = {0.f, 0.f, 0.f, 0.f};
; #pragma unroll 4
;         for (int n = 0; n < 64; ++n) {
;             const size_t ch = (size_t)bh * 64 + n;
;             u32x2 w; w.x = pk2(st.x, st.y); w.y = pk2(st.z, st.w);
;             *(u32x2*)(ST + ch * 16384 + dv * 128 + dk4) = w;
;             const f32x4 u = *(const f32x4*)(UT + ch * 16384 + dv * 128 + dk4), dc = *(const f32x4*)(DEC + ch * 128 + dk4);
;             st = dc * st + u;
;         }
;     }
; }
.LBB0_343:
	v_lshlrev_b32_e32 v0, 2, v11
	v_ashrrev_i32_e32 v4, 12, v10
	v_and_b32_e32 v6, 0x1f0, v0
	v_and_b32_e32 v7, 0xfe00, v0
	v_lshlrev_b32_e32 v0, 1, v11
	v_ashrrev_i32_e32 v5, 31, v4
	v_and_b32_e32 v8, 0x7f00, v0
	v_and_b32_e32 v9, 0xf8, v0
	v_lshlrev_b64 v[0:1], 15, v[4:5]
	v_lshlrev_b64 v[2:3], 22, v[4:5]
	v_or_b32_e32 v0, v0, v6
	v_or3_b32 v2, v2, v7, v6
	v_lshlrev_b64 v[4:5], 21, v[4:5]
	v_mov_b32_e32 v6, 0
	v_or3_b32 v4, v4, v8, v9
	s_mov_b32 s27, 16
	v_mov_b32_e32 v7, v6
	v_mov_b32_e32 v8, v6
	v_mov_b32_e32 v9, v6
	global_load_dwordx4 v[32:35], v2, s[10:11]
	global_load_dwordx4 v[48:51], v0, s[20:21]
	global_load_dwordx4 v[36:39], v2, s[12:13]
	global_load_dwordx4 v[52:55], v0, s[20:21] offset:512
	global_load_dwordx4 v[40:43], v2, s[14:15]
	global_load_dwordx4 v[56:59], v0, s[20:21] offset:1024
	global_load_dwordx4 v[44:47], v2, s[18:19]
	global_load_dwordx4 v[60:63], v0, s[20:21] offset:1536
	v_add_u32_e32 v2, 0x40000, v2
	v_add_u32_e32 v0, 0x800, v0
	global_load_dwordx4 v[64:67], v2, s[10:11]
	global_load_dwordx4 v[80:83], v0, s[20:21]
	global_load_dwordx4 v[68:71], v2, s[12:13]
	global_load_dwordx4 v[84:87], v0, s[20:21] offset:512
	global_load_dwordx4 v[72:75], v2, s[14:15]
	global_load_dwordx4 v[88:91], v0, s[20:21] offset:1024
	global_load_dwordx4 v[76:79], v2, s[18:19]
	global_load_dwordx4 v[92:95], v0, s[20:21] offset:1536
	v_add_u32_e32 v2, 0x40000, v2
	v_add_u32_e32 v0, 0x800, v0
	s_waitcnt vmcnt(8)
	s_mov_b32 s27, 7
.Lhgb_loop:
	v_cvt_pk_bf16_f32 v12, v6, v7
	v_cvt_pk_bf16_f32 v13, v8, v9
	global_store_dwordx2 v4, v[12:13], s[22:23]
	v_pk_fma_f32 v[6:7], v[6:7], v[48:49], v[32:33]
	v_pk_fma_f32 v[8:9], v[8:9], v[50:51], v[34:35]
	v_cvt_pk_bf16_f32 v14, v6, v7
	v_cvt_pk_bf16_f32 v15, v8, v9
	global_store_dwordx2 v4, v[14:15], s[24:25]
	v_pk_fma_f32 v[6:7], v[6:7], v[52:53], v[36:37]
	v_pk_fma_f32 v[8:9], v[8:9], v[54:55], v[38:39]
	v_cvt_pk_bf16_f32 v16, v6, v7
	v_cvt_pk_bf16_f32 v17, v8, v9
	global_store_dwordx2 v4, v[16:17], s[98:99]
	v_pk_fma_f32 v[6:7], v[6:7], v[56:57], v[40:41]
	v_pk_fma_f32 v[8:9], v[8:9], v[58:59], v[42:43]
	v_cvt_pk_bf16_f32 v18, v6, v7
	v_cvt_pk_bf16_f32 v19, v8, v9
	global_store_dwordx2 v4, v[18:19], s[100:101]
	v_pk_fma_f32 v[6:7], v[6:7], v[60:61], v[44:45]
	v_pk_fma_f32 v[8:9], v[8:9], v[62:63], v[46:47]
	v_add_u32_e32 v4, 0x20000, v4
	global_load_dwordx4 v[32:35], v2, s[10:11]
	global_load_dwordx4 v[48:51], v0, s[20:21]
	global_load_dwordx4 v[36:39], v2, s[12:13]
	global_load_dwordx4 v[52:55], v0, s[20:21] offset:512
	global_load_dwordx4 v[40:43], v2, s[14:15]
	global_load_dwordx4 v[56:59], v0, s[20:21] offset:1024
	global_load_dwordx4 v[44:47], v2, s[18:19]
	global_load_dwordx4 v[60:63], v0, s[20:21] offset:1536
	v_add_u32_e32 v2, 0x40000, v2
	v_add_u32_e32 v0, 0x800, v0
	s_waitcnt vmcnt(12)
	v_cvt_pk_bf16_f32 v12, v6, v7
	v_cvt_pk_bf16_f32 v13, v8, v9
	global_store_dwordx2 v4, v[12:13], s[22:23]
	v_pk_fma_f32 v[6:7], v[6:7], v[80:81], v[64:65]
	v_pk_fma_f32 v[8:9], v[8:9], v[82:83], v[66:67]
	v_cvt_pk_bf16_f32 v14, v6, v7
	v_cvt_pk_bf16_f32 v15, v8, v9
	global_store_dwordx2 v4, v[14:15], s[24:25]
	v_pk_fma_f32 v[6:7], v[6:7], v[84:85], v[68:69]
	v_pk_fma_f32 v[8:9], v[8:9], v[86:87], v[70:71]
	v_cvt_pk_bf16_f32 v16, v6, v7
	v_cvt_pk_bf16_f32 v17, v8, v9
	global_store_dwordx2 v4, v[16:17], s[98:99]
	v_pk_fma_f32 v[6:7], v[6:7], v[88:89], v[72:73]
	v_pk_fma_f32 v[8:9], v[8:9], v[90:91], v[74:75]
	v_cvt_pk_bf16_f32 v18, v6, v7
	v_cvt_pk_bf16_f32 v19, v8, v9
	global_store_dwordx2 v4, v[18:19], s[100:101]
	v_pk_fma_f32 v[6:7], v[6:7], v[92:93], v[76:77]
	v_pk_fma_f32 v[8:9], v[8:9], v[94:95], v[78:79]
	v_add_u32_e32 v4, 0x20000, v4
	global_load_dwordx4 v[64:67], v2, s[10:11]
	global_load_dwordx4 v[80:83], v0, s[20:21]
	global_load_dwordx4 v[68:71], v2, s[12:13]
	global_load_dwordx4 v[84:87], v0, s[20:21] offset:512
	global_load_dwordx4 v[72:75], v2, s[14:15]
	global_load_dwordx4 v[88:91], v0, s[20:21] offset:1024
	global_load_dwordx4 v[76:79], v2, s[18:19]
	global_load_dwordx4 v[92:95], v0, s[20:21] offset:1536
	v_add_u32_e32 v2, 0x40000, v2
	v_add_u32_e32 v0, 0x800, v0
	s_waitcnt vmcnt(12)
	s_sub_u32 s27, s27, 1
	s_cmp_lg_u32 s27, 0
	s_cbranch_scc1 .Lhgb_loop
	v_cvt_pk_bf16_f32 v12, v6, v7
	v_cvt_pk_bf16_f32 v13, v8, v9
	global_store_dwordx2 v4, v[12:13], s[22:23]
	v_pk_fma_f32 v[6:7], v[6:7], v[48:49], v[32:33]
	v_pk_fma_f32 v[8:9], v[8:9], v[50:51], v[34:35]
	v_cvt_pk_bf16_f32 v14, v6, v7
	v_cvt_pk_bf16_f32 v15, v8, v9
	global_store_dwordx2 v4, v[14:15], s[24:25]
	v_pk_fma_f32 v[6:7], v[6:7], v[52:53], v[36:37]
	v_pk_fma_f32 v[8:9], v[8:9], v[54:55], v[38:39]
	v_cvt_pk_bf16_f32 v16, v6, v7
	v_cvt_pk_bf16_f32 v17, v8, v9
	global_store_dwordx2 v4, v[16:17], s[98:99]
	v_pk_fma_f32 v[6:7], v[6:7], v[56:57], v[40:41]
	v_pk_fma_f32 v[8:9], v[8:9], v[58:59], v[42:43]
	v_cvt_pk_bf16_f32 v18, v6, v7
	v_cvt_pk_bf16_f32 v19, v8, v9
	global_store_dwordx2 v4, v[18:19], s[100:101]
	v_pk_fma_f32 v[6:7], v[6:7], v[60:61], v[44:45]
	v_pk_fma_f32 v[8:9], v[8:9], v[62:63], v[46:47]
	v_add_u32_e32 v4, 0x20000, v4
	s_waitcnt vmcnt(4)
	v_cvt_pk_bf16_f32 v12, v6, v7
	v_cvt_pk_bf16_f32 v13, v8, v9
	global_store_dwordx2 v4, v[12:13], s[22:23]
	v_pk_fma_f32 v[6:7], v[6:7], v[80:81], v[64:65]
	v_pk_fma_f32 v[8:9], v[8:9], v[82:83], v[66:67]
	v_cvt_pk_bf16_f32 v14, v6, v7
	v_cvt_pk_bf16_f32 v15, v8, v9
	global_store_dwordx2 v4, v[14:15], s[24:25]
	v_pk_fma_f32 v[6:7], v[6:7], v[84:85], v[68:69]
	v_pk_fma_f32 v[8:9], v[8:9], v[86:87], v[70:71]
	v_cvt_pk_bf16_f32 v16, v6, v7
	v_cvt_pk_bf16_f32 v17, v8, v9
	global_store_dwordx2 v4, v[16:17], s[98:99]
	v_pk_fma_f32 v[6:7], v[6:7], v[88:89], v[72:73]
	v_pk_fma_f32 v[8:9], v[8:9], v[90:91], v[74:75]
	v_cvt_pk_bf16_f32 v18, v6, v7
	v_cvt_pk_bf16_f32 v19, v8, v9
	global_store_dwordx2 v4, v[18:19], s[100:101]
	v_pk_fma_f32 v[6:7], v[6:7], v[92:93], v[76:77]
	v_pk_fma_f32 v[8:9], v[8:9], v[94:95], v[78:79]
	v_add_u32_e32 v4, 0x20000, v4
	v_add_u32_e32 v10, s74, v10
	v_cmp_lt_i32_e32 vcc, s26, v10
	s_or_b64 s[8:9], vcc, s[8:9]
	v_add_u32_e32 v11, s16, v11
	s_andn2_b64 exec, exec, s[8:9]
	s_cbranch_execnz .LBB0_343
